# first unit of the multi-unit GEMM phases also runs a cloned first K iteration with C=0 first MFMAs (original waits): no v_mov accumulator zeroing left in gate/up, QKV, q_b/kv_b unit loops
# baseline (speedup 1.0000x reference)
.Lz0_G67:
	s_add_u32 s36, s34, 0xfffe0080
	s_addc_u32 s37, s35, -1
	s_add_i32 s49, 0, 0x10000
	s_cmp_eq_u32 s48, 4
	s_cselect_b32 s39, s7, s37
	s_cselect_b32 s38, s9, s36
	s_cselect_b32 s37, s21, s45
	s_cselect_b32 s36, s25, s27
	s_add_i32 s61, 0, 0x14000
	v_add_u32_e32 v142, s49, v216
	v_add_u32_e32 v158, s61, v216
	ds_read_b128 v[130:133], v142
	ds_read_b128 v[134:137], v142 offset:1024
	ds_read_b128 v[138:141], v142 offset:2048
	ds_read_b128 v[142:145], v142 offset:3072
	ds_read_b128 v[146:149], v158
	ds_read_b128 v[150:153], v158 offset:1024
	ds_read_b128 v[154:157], v158 offset:2048
	ds_read_b128 v[158:161], v158 offset:3072
	v_lshl_add_u64 v[202:203], s[34:35], 0, v[210:211]
	s_add_i32 m0, s87, 0xc000
	ds_read_b128 v[162:165], v221
	ds_read_b128 v[166:169], v221 offset:1024
	ds_read_b128 v[170:173], v221 offset:2048
	ds_read_b128 v[174:177], v221 offset:3072
	ds_read_b128 v[178:181], v221 offset:4096
	ds_read_b128 v[182:185], v221 offset:5120
	ds_read_b128 v[186:189], v221 offset:6144
	ds_read_b128 v[190:193], v221 offset:7168
	global_load_lds_dwordx4 v[202:203], off
	v_lshl_add_u64 v[202:203], s[34:35], 0, v[208:209]
	s_add_i32 m0, s87, 0xe000
	s_nop 0
	global_load_lds_dwordx4 v[202:203], off
	s_waitcnt vmcnt(8)
	s_waitcnt lgkmcnt(0)
	s_barrier
	s_setprio 1
	s_waitcnt lgkmcnt(0)
	v_mfma_f32_16x16x32_bf16 v[126:129], v[130:133], v[162:165], 0
	v_mfma_f32_16x16x32_bf16 v[122:125], v[138:141], v[162:165], 0
	v_mfma_f32_16x16x32_bf16 v[110:113], v[130:133], v[170:173], 0
	v_mfma_f32_16x16x32_bf16 v[106:109], v[138:141], v[170:173], 0
	v_mfma_f32_16x16x32_bf16 v[94:97], v[130:133], v[178:181], 0
	v_mfma_f32_16x16x32_bf16 v[90:93], v[138:141], v[178:181], 0
	v_mfma_f32_16x16x32_bf16 v[78:81], v[130:133], v[186:189], 0
	v_mfma_f32_16x16x32_bf16 v[74:77], v[138:141], v[186:189], 0
	v_mfma_f32_16x16x32_bf16 v[126:129], v[134:137], v[166:169], v[126:129]
	v_mfma_f32_16x16x32_bf16 v[122:125], v[142:145], v[166:169], v[122:125]
	v_mfma_f32_16x16x32_bf16 v[110:113], v[134:137], v[174:177], v[110:113]
	v_mfma_f32_16x16x32_bf16 v[106:109], v[142:145], v[174:177], v[106:109]
	v_mfma_f32_16x16x32_bf16 v[94:97], v[134:137], v[182:185], v[94:97]
	v_mfma_f32_16x16x32_bf16 v[90:93], v[142:145], v[182:185], v[90:93]
	v_mfma_f32_16x16x32_bf16 v[78:81], v[134:137], v[190:193], v[78:81]
	v_mfma_f32_16x16x32_bf16 v[74:77], v[142:145], v[190:193], v[74:77]
	s_setprio 0
	s_setprio 1
	v_mfma_f32_16x16x32_bf16 v[118:121], v[146:149], v[162:165], 0
	v_mfma_f32_16x16x32_bf16 v[114:117], v[154:157], v[162:165], 0
	v_mfma_f32_16x16x32_bf16 v[102:105], v[146:149], v[170:173], 0
	v_mfma_f32_16x16x32_bf16 v[98:101], v[154:157], v[170:173], 0
	v_mfma_f32_16x16x32_bf16 v[86:89], v[146:149], v[178:181], 0
	v_mfma_f32_16x16x32_bf16 v[82:85], v[154:157], v[178:181], 0
	v_mfma_f32_16x16x32_bf16 v[70:73], v[146:149], v[186:189], 0
	v_mfma_f32_16x16x32_bf16 v[66:69], v[154:157], v[186:189], 0
	v_mfma_f32_16x16x32_bf16 v[118:121], v[150:153], v[166:169], v[118:121]
	v_mfma_f32_16x16x32_bf16 v[114:117], v[158:161], v[166:169], v[114:117]
	v_mfma_f32_16x16x32_bf16 v[102:105], v[150:153], v[174:177], v[102:105]
	v_mfma_f32_16x16x32_bf16 v[98:101], v[158:161], v[174:177], v[98:101]
	v_mfma_f32_16x16x32_bf16 v[86:89], v[150:153], v[182:185], v[86:89]
	v_mfma_f32_16x16x32_bf16 v[82:85], v[158:161], v[182:185], v[82:85]
	v_mfma_f32_16x16x32_bf16 v[70:73], v[150:153], v[190:193], v[70:73]
	v_mfma_f32_16x16x32_bf16 v[66:69], v[158:161], v[190:193], v[66:69]
	s_setprio 0
	s_barrier
	s_add_i32 s49, s49, s86
	v_lshl_add_u64 v[202:203], s[36:37], 0, v[194:195]
	s_mov_b32 m0, s49
	ds_read_b128 v[162:165], v221 offset:16384
	ds_read_b128 v[166:169], v221 offset:17408
	ds_read_b128 v[170:173], v221 offset:18432
	ds_read_b128 v[174:177], v221 offset:19456
	ds_read_b128 v[178:181], v221 offset:20480
	ds_read_b128 v[182:185], v221 offset:21504
	ds_read_b128 v[186:189], v221 offset:22528
	ds_read_b128 v[190:193], v221 offset:23552
	global_load_lds_dwordx4 v[202:203], off
	s_add_i32 m0, s49, 0x2000
	s_add_u32 s94, s36, 0x20000
	v_lshl_add_u64 v[204:205], s[36:37], 0, v[196:197]
	s_addc_u32 s95, s37, 0
	s_add_i32 s49, s61, s86
	global_load_lds_dwordx4 v[204:205], off
	v_lshl_add_u64 v[206:207], s[94:95], 0, v[194:195]
	s_mov_b32 m0, s49
	v_lshl_add_u64 v[222:223], s[38:39], 0, v[196:197]
	global_load_lds_dwordx4 v[206:207], off
	v_lshl_add_u64 v[206:207], s[94:95], 0, v[196:197]
	s_add_i32 m0, s49, 0x2000
	s_nop 0
	global_load_lds_dwordx4 v[206:207], off
	v_lshl_add_u64 v[206:207], s[38:39], 0, v[194:195]
	s_mov_b32 m0, s87
	s_nop 0
	global_load_lds_dwordx4 v[206:207], off
	s_mov_b32 m0, s68
	s_nop 0
	global_load_lds_dwordx4 v[222:223], off
	s_waitcnt vmcnt(8)
	s_waitcnt lgkmcnt(0)
	s_barrier
	s_setprio 1
	s_waitcnt lgkmcnt(0)
	v_mfma_f32_16x16x32_bf16 v[62:65], v[130:133], v[162:165], 0
	v_mfma_f32_16x16x32_bf16 v[58:61], v[138:141], v[162:165], 0
	v_mfma_f32_16x16x32_bf16 v[46:49], v[130:133], v[170:173], 0
	v_mfma_f32_16x16x32_bf16 v[42:45], v[138:141], v[170:173], 0
	v_mfma_f32_16x16x32_bf16 v[30:33], v[130:133], v[178:181], 0
	v_mfma_f32_16x16x32_bf16 v[26:29], v[138:141], v[178:181], 0
	v_mfma_f32_16x16x32_bf16 v[14:17], v[130:133], v[186:189], 0
	v_mfma_f32_16x16x32_bf16 v[10:13], v[138:141], v[186:189], 0
	v_mfma_f32_16x16x32_bf16 v[62:65], v[134:137], v[166:169], v[62:65]
	v_mfma_f32_16x16x32_bf16 v[58:61], v[142:145], v[166:169], v[58:61]
	v_mfma_f32_16x16x32_bf16 v[46:49], v[134:137], v[174:177], v[46:49]
	v_mfma_f32_16x16x32_bf16 v[42:45], v[142:145], v[174:177], v[42:45]
	v_mfma_f32_16x16x32_bf16 v[30:33], v[134:137], v[182:185], v[30:33]
	v_mfma_f32_16x16x32_bf16 v[26:29], v[142:145], v[182:185], v[26:29]
	v_mfma_f32_16x16x32_bf16 v[14:17], v[134:137], v[190:193], v[14:17]
	v_mfma_f32_16x16x32_bf16 v[10:13], v[142:145], v[190:193], v[10:13]
	s_setprio 0
	s_setprio 1
	v_mfma_f32_16x16x32_bf16 v[54:57], v[146:149], v[162:165], 0
	v_mfma_f32_16x16x32_bf16 v[50:53], v[154:157], v[162:165], 0
	v_mfma_f32_16x16x32_bf16 v[38:41], v[146:149], v[170:173], 0
	v_mfma_f32_16x16x32_bf16 v[34:37], v[154:157], v[170:173], 0
	v_mfma_f32_16x16x32_bf16 v[22:25], v[146:149], v[178:181], 0
	v_mfma_f32_16x16x32_bf16 v[18:21], v[154:157], v[178:181], 0
	v_mfma_f32_16x16x32_bf16 v[6:9], v[146:149], v[186:189], 0
	v_mfma_f32_16x16x32_bf16 v[2:5], v[154:157], v[186:189], 0
	v_mfma_f32_16x16x32_bf16 v[54:57], v[150:153], v[166:169], v[54:57]
	v_mfma_f32_16x16x32_bf16 v[50:53], v[158:161], v[166:169], v[50:53]
	v_mfma_f32_16x16x32_bf16 v[38:41], v[150:153], v[174:177], v[38:41]
	v_mfma_f32_16x16x32_bf16 v[34:37], v[158:161], v[174:177], v[34:37]
	v_mfma_f32_16x16x32_bf16 v[22:25], v[150:153], v[182:185], v[22:25]
	v_mfma_f32_16x16x32_bf16 v[18:21], v[158:161], v[182:185], v[18:21]
	v_mfma_f32_16x16x32_bf16 v[6:9], v[150:153], v[190:193], v[6:9]
	v_mfma_f32_16x16x32_bf16 v[2:5], v[158:161], v[190:193], v[2:5]
	s_setprio 0
	s_barrier
	s_add_i32 s49, 0, 0x18000
	s_add_i32 s61, 0, 0x1c000
	v_add_u32_e32 v142, s49, v216
	v_add_u32_e32 v158, s61, v216
	ds_read_b128 v[130:133], v142
	ds_read_b128 v[134:137], v142 offset:1024
	ds_read_b128 v[138:141], v142 offset:2048
	ds_read_b128 v[142:145], v142 offset:3072
	ds_read_b128 v[146:149], v158
	ds_read_b128 v[150:153], v158 offset:1024
	ds_read_b128 v[154:157], v158 offset:2048
	ds_read_b128 v[158:161], v158 offset:3072
	s_add_u32 s38, s38, 0x20000
	s_addc_u32 s39, s39, 0
	s_mov_b32 m0, s69
	v_lshl_add_u64 v[226:227], s[38:39], 0, v[194:195]
	ds_read_b128 v[162:165], v221 offset:32768
	ds_read_b128 v[166:169], v221 offset:33792
	ds_read_b128 v[170:173], v221 offset:34816
	ds_read_b128 v[174:177], v221 offset:35840
	ds_read_b128 v[178:181], v221 offset:36864
	ds_read_b128 v[182:185], v221 offset:37888
	ds_read_b128 v[186:189], v221 offset:38912
	ds_read_b128 v[190:193], v221 offset:39936
	global_load_lds_dwordx4 v[226:227], off
	v_lshl_add_u64 v[226:227], s[38:39], 0, v[196:197]
	s_mov_b32 m0, s70
	s_nop 0
	global_load_lds_dwordx4 v[226:227], off
	s_waitcnt vmcnt(8)
	s_waitcnt lgkmcnt(0)
	s_barrier
	s_setprio 1
	s_waitcnt lgkmcnt(0)
	v_mfma_f32_16x16x32_bf16 v[126:129], v[130:133], v[162:165], v[126:129]
	v_mfma_f32_16x16x32_bf16 v[122:125], v[138:141], v[162:165], v[122:125]
	v_mfma_f32_16x16x32_bf16 v[110:113], v[130:133], v[170:173], v[110:113]
	v_mfma_f32_16x16x32_bf16 v[106:109], v[138:141], v[170:173], v[106:109]
	v_mfma_f32_16x16x32_bf16 v[94:97], v[130:133], v[178:181], v[94:97]
	v_mfma_f32_16x16x32_bf16 v[90:93], v[138:141], v[178:181], v[90:93]
	v_mfma_f32_16x16x32_bf16 v[78:81], v[130:133], v[186:189], v[78:81]
	v_mfma_f32_16x16x32_bf16 v[74:77], v[138:141], v[186:189], v[74:77]
	v_mfma_f32_16x16x32_bf16 v[126:129], v[134:137], v[166:169], v[126:129]
	v_mfma_f32_16x16x32_bf16 v[122:125], v[142:145], v[166:169], v[122:125]
	v_mfma_f32_16x16x32_bf16 v[110:113], v[134:137], v[174:177], v[110:113]
	v_mfma_f32_16x16x32_bf16 v[106:109], v[142:145], v[174:177], v[106:109]
	v_mfma_f32_16x16x32_bf16 v[94:97], v[134:137], v[182:185], v[94:97]
	v_mfma_f32_16x16x32_bf16 v[90:93], v[142:145], v[182:185], v[90:93]
	v_mfma_f32_16x16x32_bf16 v[78:81], v[134:137], v[190:193], v[78:81]
	v_mfma_f32_16x16x32_bf16 v[74:77], v[142:145], v[190:193], v[74:77]
	s_setprio 0
	s_setprio 1
	v_mfma_f32_16x16x32_bf16 v[118:121], v[146:149], v[162:165], v[118:121]
	v_mfma_f32_16x16x32_bf16 v[114:117], v[154:157], v[162:165], v[114:117]
	v_mfma_f32_16x16x32_bf16 v[102:105], v[146:149], v[170:173], v[102:105]
	v_mfma_f32_16x16x32_bf16 v[98:101], v[154:157], v[170:173], v[98:101]
	v_mfma_f32_16x16x32_bf16 v[86:89], v[146:149], v[178:181], v[86:89]
	v_mfma_f32_16x16x32_bf16 v[82:85], v[154:157], v[178:181], v[82:85]
	v_mfma_f32_16x16x32_bf16 v[70:73], v[146:149], v[186:189], v[70:73]
	v_mfma_f32_16x16x32_bf16 v[66:69], v[154:157], v[186:189], v[66:69]
	v_mfma_f32_16x16x32_bf16 v[118:121], v[150:153], v[166:169], v[118:121]
	v_mfma_f32_16x16x32_bf16 v[114:117], v[158:161], v[166:169], v[114:117]
	v_mfma_f32_16x16x32_bf16 v[102:105], v[150:153], v[174:177], v[102:105]
	v_mfma_f32_16x16x32_bf16 v[98:101], v[158:161], v[174:177], v[98:101]
	v_mfma_f32_16x16x32_bf16 v[86:89], v[150:153], v[182:185], v[86:89]
	v_mfma_f32_16x16x32_bf16 v[82:85], v[158:161], v[182:185], v[82:85]
	v_mfma_f32_16x16x32_bf16 v[70:73], v[150:153], v[190:193], v[70:73]
	v_mfma_f32_16x16x32_bf16 v[66:69], v[158:161], v[190:193], v[66:69]
	s_setprio 0
	s_barrier
	s_add_i32 s38, s49, s86
	v_lshl_add_u64 v[202:203], v[202:203], 0, s[54:55]
	s_mov_b32 m0, s38
	ds_read_b128 v[162:165], v221 offset:49152
	ds_read_b128 v[166:169], v221 offset:50176
	ds_read_b128 v[170:173], v221 offset:51200
	ds_read_b128 v[174:177], v221 offset:52224
	ds_read_b128 v[178:181], v221 offset:53248
	ds_read_b128 v[182:185], v221 offset:54272
	ds_read_b128 v[186:189], v221 offset:55296
	ds_read_b128 v[190:193], v221 offset:56320
	global_load_lds_dwordx4 v[202:203], off
	s_add_i32 m0, s38, 0x2000
	s_add_u32 s36, s36, 0x20080
	v_lshl_add_u64 v[202:203], v[204:205], 0, s[54:55]
	s_addc_u32 s37, s37, 0
	s_add_i32 s38, s61, s86
	global_load_lds_dwordx4 v[202:203], off
	v_lshl_add_u64 v[202:203], s[36:37], 0, v[194:195]
	s_mov_b32 m0, s38
	s_nop 0
	global_load_lds_dwordx4 v[202:203], off
	v_lshl_add_u64 v[202:203], s[36:37], 0, v[196:197]
	s_add_i32 m0, s38, 0x2000
	s_nop 0
	global_load_lds_dwordx4 v[202:203], off
	v_lshl_add_u64 v[202:203], v[206:207], 0, s[54:55]
	s_mov_b32 m0, s73
	s_nop 0
	global_load_lds_dwordx4 v[202:203], off
	v_lshl_add_u64 v[202:203], v[222:223], 0, s[54:55]
	s_mov_b32 m0, s89
	s_nop 0
	global_load_lds_dwordx4 v[202:203], off
	s_waitcnt vmcnt(8)
	s_waitcnt lgkmcnt(0)
	s_barrier
	s_setprio 1
	s_waitcnt lgkmcnt(0)
	v_mfma_f32_16x16x32_bf16 v[62:65], v[130:133], v[162:165], v[62:65]
	v_mfma_f32_16x16x32_bf16 v[58:61], v[138:141], v[162:165], v[58:61]
	v_mfma_f32_16x16x32_bf16 v[46:49], v[130:133], v[170:173], v[46:49]
	v_mfma_f32_16x16x32_bf16 v[42:45], v[138:141], v[170:173], v[42:45]
	v_mfma_f32_16x16x32_bf16 v[30:33], v[130:133], v[178:181], v[30:33]
	v_mfma_f32_16x16x32_bf16 v[26:29], v[138:141], v[178:181], v[26:29]
	v_mfma_f32_16x16x32_bf16 v[14:17], v[130:133], v[186:189], v[14:17]
	v_mfma_f32_16x16x32_bf16 v[10:13], v[138:141], v[186:189], v[10:13]
	v_mfma_f32_16x16x32_bf16 v[62:65], v[134:137], v[166:169], v[62:65]
	v_mfma_f32_16x16x32_bf16 v[58:61], v[142:145], v[166:169], v[58:61]
	v_mfma_f32_16x16x32_bf16 v[46:49], v[134:137], v[174:177], v[46:49]
	v_mfma_f32_16x16x32_bf16 v[42:45], v[142:145], v[174:177], v[42:45]
	v_mfma_f32_16x16x32_bf16 v[30:33], v[134:137], v[182:185], v[30:33]
	v_mfma_f32_16x16x32_bf16 v[26:29], v[142:145], v[182:185], v[26:29]
	v_mfma_f32_16x16x32_bf16 v[14:17], v[134:137], v[190:193], v[14:17]
	v_mfma_f32_16x16x32_bf16 v[10:13], v[142:145], v[190:193], v[10:13]
	s_setprio 0
	s_setprio 1
	v_mfma_f32_16x16x32_bf16 v[54:57], v[146:149], v[162:165], v[54:57]
	v_mfma_f32_16x16x32_bf16 v[50:53], v[154:157], v[162:165], v[50:53]
	v_mfma_f32_16x16x32_bf16 v[38:41], v[146:149], v[170:173], v[38:41]
	v_mfma_f32_16x16x32_bf16 v[34:37], v[154:157], v[170:173], v[34:37]
	v_mfma_f32_16x16x32_bf16 v[22:25], v[146:149], v[178:181], v[22:25]
	v_mfma_f32_16x16x32_bf16 v[18:21], v[154:157], v[178:181], v[18:21]
	v_mfma_f32_16x16x32_bf16 v[6:9], v[146:149], v[186:189], v[6:9]
	v_mfma_f32_16x16x32_bf16 v[2:5], v[154:157], v[186:189], v[2:5]
	v_mfma_f32_16x16x32_bf16 v[54:57], v[150:153], v[166:169], v[54:57]
	v_mfma_f32_16x16x32_bf16 v[50:53], v[158:161], v[166:169], v[50:53]
	v_mfma_f32_16x16x32_bf16 v[38:41], v[150:153], v[174:177], v[38:41]
	v_mfma_f32_16x16x32_bf16 v[34:37], v[158:161], v[174:177], v[34:37]
	v_mfma_f32_16x16x32_bf16 v[22:25], v[150:153], v[182:185], v[22:25]
	v_mfma_f32_16x16x32_bf16 v[18:21], v[158:161], v[182:185], v[18:21]
	v_mfma_f32_16x16x32_bf16 v[6:9], v[150:153], v[190:193], v[6:9]
	v_mfma_f32_16x16x32_bf16 v[2:5], v[158:161], v[190:193], v[2:5]
	s_setprio 0
	s_barrier
	s_add_i32 s48, s48, 2
	s_add_u32 s27, s27, 0x100
	s_addc_u32 s45, s45, 0
	s_add_u32 s34, s34, 0x100
	s_addc_u32 s35, s35, 0
	s_cmp_gt_u32 s48, 5
	s_cbranch_scc1 .Lpeel_exit_G67
	s_branch .LBB0_430

.Lz0_G1:
	s_add_u32 s80, s8, 0xfff80080
	s_addc_u32 s81, s9, -1
	s_add_i32 s87, 0, 0x10000
	s_cmp_eq_u32 s86, 28
	s_cselect_b32 s83, s11, s81
	s_cselect_b32 s82, s35, s80
	s_cselect_b32 s81, s31, s85
	s_cselect_b32 s80, s79, s84
	s_add_i32 s92, 0, 0x14000
	v_add_u32_e32 v142, s87, v228
	v_add_u32_e32 v158, s92, v228
	ds_read_b128 v[126:129], v142
	ds_read_b128 v[134:137], v142 offset:1024
	ds_read_b128 v[138:141], v142 offset:2048
	ds_read_b128 v[142:145], v142 offset:3072
	ds_read_b128 v[146:149], v158
	ds_read_b128 v[150:153], v158 offset:1024
	ds_read_b128 v[154:157], v158 offset:2048
	ds_read_b128 v[158:161], v158 offset:3072
	v_lshl_add_u64 v[202:203], s[8:9], 0, v[210:211]
	s_add_i32 m0, s61, 0xc000
	ds_read_b128 v[162:165], v233
	ds_read_b128 v[166:169], v233 offset:1024
	ds_read_b128 v[170:173], v233 offset:2048
	ds_read_b128 v[174:177], v233 offset:3072
	ds_read_b128 v[178:181], v233 offset:4096
	ds_read_b128 v[182:185], v233 offset:5120
	ds_read_b128 v[186:189], v233 offset:6144
	ds_read_b128 v[190:193], v233 offset:7168
	global_load_lds_dwordx4 v[202:203], off
	v_lshl_add_u64 v[202:203], s[8:9], 0, v[208:209]
	s_add_i32 m0, s61, 0xe000
	s_nop 0
	global_load_lds_dwordx4 v[202:203], off
	s_waitcnt vmcnt(8)
	s_waitcnt lgkmcnt(0)
	s_barrier
	s_setprio 1
	s_waitcnt lgkmcnt(0)
	v_mfma_f32_16x16x32_bf16 v[130:133], v[126:129], v[162:165], 0
	v_mfma_f32_16x16x32_bf16 v[122:125], v[138:141], v[162:165], 0
	v_mfma_f32_16x16x32_bf16 v[110:113], v[126:129], v[170:173], 0
	v_mfma_f32_16x16x32_bf16 v[106:109], v[138:141], v[170:173], 0
	v_mfma_f32_16x16x32_bf16 v[94:97], v[126:129], v[178:181], 0
	v_mfma_f32_16x16x32_bf16 v[90:93], v[138:141], v[178:181], 0
	v_mfma_f32_16x16x32_bf16 v[78:81], v[126:129], v[186:189], 0
	v_mfma_f32_16x16x32_bf16 v[74:77], v[138:141], v[186:189], 0
	v_mfma_f32_16x16x32_bf16 v[130:133], v[134:137], v[166:169], v[130:133]
	v_mfma_f32_16x16x32_bf16 v[122:125], v[142:145], v[166:169], v[122:125]
	v_mfma_f32_16x16x32_bf16 v[110:113], v[134:137], v[174:177], v[110:113]
	v_mfma_f32_16x16x32_bf16 v[106:109], v[142:145], v[174:177], v[106:109]
	v_mfma_f32_16x16x32_bf16 v[94:97], v[134:137], v[182:185], v[94:97]
	v_mfma_f32_16x16x32_bf16 v[90:93], v[142:145], v[182:185], v[90:93]
	v_mfma_f32_16x16x32_bf16 v[78:81], v[134:137], v[190:193], v[78:81]
	v_mfma_f32_16x16x32_bf16 v[74:77], v[142:145], v[190:193], v[74:77]
	s_setprio 0
	s_setprio 1
	v_mfma_f32_16x16x32_bf16 v[118:121], v[146:149], v[162:165], 0
	v_mfma_f32_16x16x32_bf16 v[114:117], v[154:157], v[162:165], 0
	v_mfma_f32_16x16x32_bf16 v[102:105], v[146:149], v[170:173], 0
	v_mfma_f32_16x16x32_bf16 v[98:101], v[154:157], v[170:173], 0
	v_mfma_f32_16x16x32_bf16 v[86:89], v[146:149], v[178:181], 0
	v_mfma_f32_16x16x32_bf16 v[82:85], v[154:157], v[178:181], 0
	v_mfma_f32_16x16x32_bf16 v[70:73], v[146:149], v[186:189], 0
	v_mfma_f32_16x16x32_bf16 v[66:69], v[154:157], v[186:189], 0
	v_mfma_f32_16x16x32_bf16 v[118:121], v[150:153], v[166:169], v[118:121]
	v_mfma_f32_16x16x32_bf16 v[114:117], v[158:161], v[166:169], v[114:117]
	v_mfma_f32_16x16x32_bf16 v[102:105], v[150:153], v[174:177], v[102:105]
	v_mfma_f32_16x16x32_bf16 v[98:101], v[158:161], v[174:177], v[98:101]
	v_mfma_f32_16x16x32_bf16 v[86:89], v[150:153], v[182:185], v[86:89]
	v_mfma_f32_16x16x32_bf16 v[82:85], v[158:161], v[182:185], v[82:85]
	v_mfma_f32_16x16x32_bf16 v[70:73], v[150:153], v[190:193], v[70:73]
	v_mfma_f32_16x16x32_bf16 v[66:69], v[158:161], v[190:193], v[66:69]
	s_setprio 0
	s_barrier
	s_add_i32 s87, s87, s95
	v_lshl_add_u64 v[202:203], s[80:81], 0, v[194:195]
	s_mov_b32 m0, s87
	ds_read_b128 v[162:165], v233 offset:16384
	ds_read_b128 v[166:169], v233 offset:17408
	ds_read_b128 v[170:173], v233 offset:18432
	ds_read_b128 v[174:177], v233 offset:19456
	ds_read_b128 v[178:181], v233 offset:20480
	ds_read_b128 v[182:185], v233 offset:21504
	ds_read_b128 v[186:189], v233 offset:22528
	ds_read_b128 v[190:193], v233 offset:23552
	global_load_lds_dwordx4 v[202:203], off
	s_add_i32 m0, s87, 0x2000
	s_add_u32 vcc_lo, s80, 0x80000
	v_lshl_add_u64 v[204:205], s[80:81], 0, v[196:197]
	s_addc_u32 vcc_hi, s81, 0
	s_add_i32 s87, s92, s95
	global_load_lds_dwordx4 v[204:205], off
	v_lshl_add_u64 v[206:207], vcc, 0, v[194:195]
	s_mov_b32 m0, s87
	v_lshl_add_u64 v[214:215], s[82:83], 0, v[196:197]
	global_load_lds_dwordx4 v[206:207], off
	v_lshl_add_u64 v[206:207], vcc, 0, v[196:197]
	s_add_i32 m0, s87, 0x2000
	s_nop 0
	global_load_lds_dwordx4 v[206:207], off
	v_lshl_add_u64 v[206:207], s[82:83], 0, v[194:195]
	s_mov_b32 m0, s61
	s_nop 0
	global_load_lds_dwordx4 v[206:207], off
	s_mov_b32 m0, s44
	s_nop 0
	global_load_lds_dwordx4 v[214:215], off
	s_waitcnt vmcnt(8)
	s_waitcnt lgkmcnt(0)
	s_barrier
	s_setprio 1
	s_waitcnt lgkmcnt(0)
	v_mfma_f32_16x16x32_bf16 v[62:65], v[126:129], v[162:165], 0
	v_mfma_f32_16x16x32_bf16 v[58:61], v[138:141], v[162:165], 0
	v_mfma_f32_16x16x32_bf16 v[46:49], v[126:129], v[170:173], 0
	v_mfma_f32_16x16x32_bf16 v[42:45], v[138:141], v[170:173], 0
	v_mfma_f32_16x16x32_bf16 v[30:33], v[126:129], v[178:181], 0
	v_mfma_f32_16x16x32_bf16 v[26:29], v[138:141], v[178:181], 0
	v_mfma_f32_16x16x32_bf16 v[14:17], v[126:129], v[186:189], 0
	v_mfma_f32_16x16x32_bf16 v[10:13], v[138:141], v[186:189], 0
	v_mfma_f32_16x16x32_bf16 v[62:65], v[134:137], v[166:169], v[62:65]
	v_mfma_f32_16x16x32_bf16 v[58:61], v[142:145], v[166:169], v[58:61]
	v_mfma_f32_16x16x32_bf16 v[46:49], v[134:137], v[174:177], v[46:49]
	v_mfma_f32_16x16x32_bf16 v[42:45], v[142:145], v[174:177], v[42:45]
	v_mfma_f32_16x16x32_bf16 v[30:33], v[134:137], v[182:185], v[30:33]
	v_mfma_f32_16x16x32_bf16 v[26:29], v[142:145], v[182:185], v[26:29]
	v_mfma_f32_16x16x32_bf16 v[14:17], v[134:137], v[190:193], v[14:17]
	v_mfma_f32_16x16x32_bf16 v[10:13], v[142:145], v[190:193], v[10:13]
	s_setprio 0
	s_setprio 1
	v_mfma_f32_16x16x32_bf16 v[54:57], v[146:149], v[162:165], 0
	v_mfma_f32_16x16x32_bf16 v[50:53], v[154:157], v[162:165], 0
	v_mfma_f32_16x16x32_bf16 v[38:41], v[146:149], v[170:173], 0
	v_mfma_f32_16x16x32_bf16 v[34:37], v[154:157], v[170:173], 0
	v_mfma_f32_16x16x32_bf16 v[22:25], v[146:149], v[178:181], 0
	v_mfma_f32_16x16x32_bf16 v[18:21], v[154:157], v[178:181], 0
	v_mfma_f32_16x16x32_bf16 v[6:9], v[146:149], v[186:189], 0
	v_mfma_f32_16x16x32_bf16 v[2:5], v[154:157], v[186:189], 0
	v_mfma_f32_16x16x32_bf16 v[54:57], v[150:153], v[166:169], v[54:57]
	v_mfma_f32_16x16x32_bf16 v[50:53], v[158:161], v[166:169], v[50:53]
	v_mfma_f32_16x16x32_bf16 v[38:41], v[150:153], v[174:177], v[38:41]
	v_mfma_f32_16x16x32_bf16 v[34:37], v[158:161], v[174:177], v[34:37]
	v_mfma_f32_16x16x32_bf16 v[22:25], v[150:153], v[182:185], v[22:25]
	v_mfma_f32_16x16x32_bf16 v[18:21], v[158:161], v[182:185], v[18:21]
	v_mfma_f32_16x16x32_bf16 v[6:9], v[150:153], v[190:193], v[6:9]
	v_mfma_f32_16x16x32_bf16 v[2:5], v[158:161], v[190:193], v[2:5]
	s_setprio 0
	s_barrier
	s_add_i32 s87, 0, 0x18000
	s_add_i32 s92, 0, 0x1c000
	v_add_u32_e32 v142, s87, v228
	v_add_u32_e32 v158, s92, v228
	ds_read_b128 v[126:129], v142
	ds_read_b128 v[134:137], v142 offset:1024
	ds_read_b128 v[138:141], v142 offset:2048
	ds_read_b128 v[142:145], v142 offset:3072
	ds_read_b128 v[146:149], v158
	ds_read_b128 v[150:153], v158 offset:1024
	ds_read_b128 v[154:157], v158 offset:2048
	ds_read_b128 v[158:161], v158 offset:3072
	s_add_u32 s82, s82, 0x80000
	s_addc_u32 s83, s83, 0
	s_mov_b32 m0, s45
	v_lshl_add_u64 v[216:217], s[82:83], 0, v[194:195]
	ds_read_b128 v[162:165], v233 offset:32768
	ds_read_b128 v[166:169], v233 offset:33792
	ds_read_b128 v[170:173], v233 offset:34816
	ds_read_b128 v[174:177], v233 offset:35840
	ds_read_b128 v[178:181], v233 offset:36864
	ds_read_b128 v[182:185], v233 offset:37888
	ds_read_b128 v[186:189], v233 offset:38912
	ds_read_b128 v[190:193], v233 offset:39936
	global_load_lds_dwordx4 v[216:217], off
	v_lshl_add_u64 v[216:217], s[82:83], 0, v[196:197]
	s_mov_b32 m0, s88
	s_nop 0
	global_load_lds_dwordx4 v[216:217], off
	s_waitcnt vmcnt(8)
	s_waitcnt lgkmcnt(0)
	s_barrier
	s_setprio 1
	s_waitcnt lgkmcnt(0)
	v_mfma_f32_16x16x32_bf16 v[130:133], v[126:129], v[162:165], v[130:133]
	v_mfma_f32_16x16x32_bf16 v[122:125], v[138:141], v[162:165], v[122:125]
	v_mfma_f32_16x16x32_bf16 v[110:113], v[126:129], v[170:173], v[110:113]
	v_mfma_f32_16x16x32_bf16 v[106:109], v[138:141], v[170:173], v[106:109]
	v_mfma_f32_16x16x32_bf16 v[94:97], v[126:129], v[178:181], v[94:97]
	v_mfma_f32_16x16x32_bf16 v[90:93], v[138:141], v[178:181], v[90:93]
	v_mfma_f32_16x16x32_bf16 v[78:81], v[126:129], v[186:189], v[78:81]
	v_mfma_f32_16x16x32_bf16 v[74:77], v[138:141], v[186:189], v[74:77]
	v_mfma_f32_16x16x32_bf16 v[130:133], v[134:137], v[166:169], v[130:133]
	v_mfma_f32_16x16x32_bf16 v[122:125], v[142:145], v[166:169], v[122:125]
	v_mfma_f32_16x16x32_bf16 v[110:113], v[134:137], v[174:177], v[110:113]
	v_mfma_f32_16x16x32_bf16 v[106:109], v[142:145], v[174:177], v[106:109]
	v_mfma_f32_16x16x32_bf16 v[94:97], v[134:137], v[182:185], v[94:97]
	v_mfma_f32_16x16x32_bf16 v[90:93], v[142:145], v[182:185], v[90:93]
	v_mfma_f32_16x16x32_bf16 v[78:81], v[134:137], v[190:193], v[78:81]
	v_mfma_f32_16x16x32_bf16 v[74:77], v[142:145], v[190:193], v[74:77]
	s_setprio 0
	s_setprio 1
	v_mfma_f32_16x16x32_bf16 v[118:121], v[146:149], v[162:165], v[118:121]
	v_mfma_f32_16x16x32_bf16 v[114:117], v[154:157], v[162:165], v[114:117]
	v_mfma_f32_16x16x32_bf16 v[102:105], v[146:149], v[170:173], v[102:105]
	v_mfma_f32_16x16x32_bf16 v[98:101], v[154:157], v[170:173], v[98:101]
	v_mfma_f32_16x16x32_bf16 v[86:89], v[146:149], v[178:181], v[86:89]
	v_mfma_f32_16x16x32_bf16 v[82:85], v[154:157], v[178:181], v[82:85]
	v_mfma_f32_16x16x32_bf16 v[70:73], v[146:149], v[186:189], v[70:73]
	v_mfma_f32_16x16x32_bf16 v[66:69], v[154:157], v[186:189], v[66:69]
	v_mfma_f32_16x16x32_bf16 v[118:121], v[150:153], v[166:169], v[118:121]
	v_mfma_f32_16x16x32_bf16 v[114:117], v[158:161], v[166:169], v[114:117]
	v_mfma_f32_16x16x32_bf16 v[102:105], v[150:153], v[174:177], v[102:105]
	v_mfma_f32_16x16x32_bf16 v[98:101], v[158:161], v[174:177], v[98:101]
	v_mfma_f32_16x16x32_bf16 v[86:89], v[150:153], v[182:185], v[86:89]
	v_mfma_f32_16x16x32_bf16 v[82:85], v[158:161], v[182:185], v[82:85]
	v_mfma_f32_16x16x32_bf16 v[70:73], v[150:153], v[190:193], v[70:73]
	v_mfma_f32_16x16x32_bf16 v[66:69], v[158:161], v[190:193], v[66:69]
	s_setprio 0
	s_barrier
	s_add_i32 s82, s87, s95
	v_lshl_add_u64 v[202:203], v[202:203], 0, s[54:55]
	s_mov_b32 m0, s82
	ds_read_b128 v[162:165], v233 offset:49152
	ds_read_b128 v[166:169], v233 offset:50176
	ds_read_b128 v[170:173], v233 offset:51200
	ds_read_b128 v[174:177], v233 offset:52224
	ds_read_b128 v[178:181], v233 offset:53248
	ds_read_b128 v[182:185], v233 offset:54272
	ds_read_b128 v[186:189], v233 offset:55296
	ds_read_b128 v[190:193], v233 offset:56320
	global_load_lds_dwordx4 v[202:203], off
	s_add_i32 m0, s82, 0x2000
	s_add_u32 s80, s80, 0x80080
	v_lshl_add_u64 v[202:203], v[204:205], 0, s[54:55]
	s_addc_u32 s81, s81, 0
	s_add_i32 s82, s92, s95
	global_load_lds_dwordx4 v[202:203], off
	v_lshl_add_u64 v[202:203], s[80:81], 0, v[194:195]
	s_mov_b32 m0, s82
	s_nop 0
	global_load_lds_dwordx4 v[202:203], off
	v_lshl_add_u64 v[202:203], s[80:81], 0, v[196:197]
	s_add_i32 m0, s82, 0x2000
	s_nop 0
	global_load_lds_dwordx4 v[202:203], off
	v_lshl_add_u64 v[202:203], v[206:207], 0, s[54:55]
	s_mov_b32 m0, s48
	s_nop 0
	global_load_lds_dwordx4 v[202:203], off
	v_lshl_add_u64 v[202:203], v[214:215], 0, s[54:55]
	s_mov_b32 m0, s49
	s_nop 0
	global_load_lds_dwordx4 v[202:203], off
	s_waitcnt vmcnt(8)
	s_waitcnt lgkmcnt(0)
	s_barrier
	s_setprio 1
	s_waitcnt lgkmcnt(0)
	v_mfma_f32_16x16x32_bf16 v[62:65], v[126:129], v[162:165], v[62:65]
	v_mfma_f32_16x16x32_bf16 v[58:61], v[138:141], v[162:165], v[58:61]
	v_mfma_f32_16x16x32_bf16 v[46:49], v[126:129], v[170:173], v[46:49]
	v_mfma_f32_16x16x32_bf16 v[42:45], v[138:141], v[170:173], v[42:45]
	v_mfma_f32_16x16x32_bf16 v[30:33], v[126:129], v[178:181], v[30:33]
	v_mfma_f32_16x16x32_bf16 v[26:29], v[138:141], v[178:181], v[26:29]
	v_mfma_f32_16x16x32_bf16 v[14:17], v[126:129], v[186:189], v[14:17]
	v_mfma_f32_16x16x32_bf16 v[10:13], v[138:141], v[186:189], v[10:13]
	v_mfma_f32_16x16x32_bf16 v[62:65], v[134:137], v[166:169], v[62:65]
	v_mfma_f32_16x16x32_bf16 v[58:61], v[142:145], v[166:169], v[58:61]
	v_mfma_f32_16x16x32_bf16 v[46:49], v[134:137], v[174:177], v[46:49]
	v_mfma_f32_16x16x32_bf16 v[42:45], v[142:145], v[174:177], v[42:45]
	v_mfma_f32_16x16x32_bf16 v[30:33], v[134:137], v[182:185], v[30:33]
	v_mfma_f32_16x16x32_bf16 v[26:29], v[142:145], v[182:185], v[26:29]
	v_mfma_f32_16x16x32_bf16 v[14:17], v[134:137], v[190:193], v[14:17]
	v_mfma_f32_16x16x32_bf16 v[10:13], v[142:145], v[190:193], v[10:13]
	s_setprio 0
	s_setprio 1
	v_mfma_f32_16x16x32_bf16 v[54:57], v[146:149], v[162:165], v[54:57]
	v_mfma_f32_16x16x32_bf16 v[50:53], v[154:157], v[162:165], v[50:53]
	v_mfma_f32_16x16x32_bf16 v[38:41], v[146:149], v[170:173], v[38:41]
	v_mfma_f32_16x16x32_bf16 v[34:37], v[154:157], v[170:173], v[34:37]
	v_mfma_f32_16x16x32_bf16 v[22:25], v[146:149], v[178:181], v[22:25]
	v_mfma_f32_16x16x32_bf16 v[18:21], v[154:157], v[178:181], v[18:21]
	v_mfma_f32_16x16x32_bf16 v[6:9], v[146:149], v[186:189], v[6:9]
	v_mfma_f32_16x16x32_bf16 v[2:5], v[154:157], v[186:189], v[2:5]
	v_mfma_f32_16x16x32_bf16 v[54:57], v[150:153], v[166:169], v[54:57]
	v_mfma_f32_16x16x32_bf16 v[50:53], v[158:161], v[166:169], v[50:53]
	v_mfma_f32_16x16x32_bf16 v[38:41], v[150:153], v[174:177], v[38:41]
	v_mfma_f32_16x16x32_bf16 v[34:37], v[158:161], v[174:177], v[34:37]
	v_mfma_f32_16x16x32_bf16 v[22:25], v[150:153], v[182:185], v[22:25]
	v_mfma_f32_16x16x32_bf16 v[18:21], v[158:161], v[182:185], v[18:21]
	v_mfma_f32_16x16x32_bf16 v[6:9], v[150:153], v[190:193], v[6:9]
	v_mfma_f32_16x16x32_bf16 v[2:5], v[158:161], v[190:193], v[2:5]
	s_setprio 0
	s_barrier
	s_add_i32 s86, s86, 2
	s_add_u32 s84, s84, 0x100
	s_addc_u32 s85, s85, 0
	s_add_u32 s8, s8, 0x100
	s_addc_u32 s9, s9, 0
	s_cmp_gt_u32 s86, 29
	s_cbranch_scc1 .Lpeel_exit_G1
	s_branch .LBB0_605

.Lz0_G3:
	s_add_u32 s28, s26, 0xfff80080
	s_addc_u32 s29, s27, -1
	s_add_i32 s61, 0, 0x10000
	s_cmp_eq_u32 s49, 28
	s_cselect_b32 s31, s19, s29
	s_cselect_b32 s30, s33, s28
	v_add_u32_e32 v141, s61, v138
	s_cselect_b32 s29, s17, s48
	s_cselect_b32 s28, s44, s45
	s_add_i32 s73, 0, 0x14000
	ds_read_b128 v[142:145], v141
	ds_read_b128 v[146:149], v141 offset:1024
	ds_read_b128 v[150:153], v141 offset:2048
	ds_read_b128 v[154:157], v141 offset:3072
	v_add_u32_e32 v141, s73, v138
	ds_read_b128 v[158:161], v141
	ds_read_b128 v[162:165], v141 offset:1024
	ds_read_b128 v[166:169], v141 offset:2048
	ds_read_b128 v[170:173], v141 offset:3072
	v_lshl_add_u64 v[206:207], s[26:27], 0, v[134:135]
	s_add_i32 m0, s82, 0xc000
	ds_read_b128 v[174:177], v140
	ds_read_b128 v[178:181], v140 offset:1024
	ds_read_b128 v[182:185], v140 offset:2048
	ds_read_b128 v[186:189], v140 offset:3072
	ds_read_b128 v[190:193], v140 offset:4096
	ds_read_b128 v[194:197], v140 offset:5120
	ds_read_b128 v[198:201], v140 offset:6144
	ds_read_b128 v[202:205], v140 offset:7168
	global_load_lds_dwordx4 v[206:207], off
	v_lshl_add_u64 v[206:207], s[26:27], 0, v[132:133]
	s_add_i32 m0, s82, 0xe000
	s_nop 0
	global_load_lds_dwordx4 v[206:207], off
	s_waitcnt vmcnt(8)
	s_waitcnt lgkmcnt(0)
	s_barrier
	s_setprio 1
	s_waitcnt lgkmcnt(0)
	v_mfma_f32_16x16x32_bf16 v[126:129], v[142:145], v[174:177], 0
	v_mfma_f32_16x16x32_bf16 v[118:121], v[150:153], v[174:177], 0
	v_mfma_f32_16x16x32_bf16 v[110:113], v[142:145], v[182:185], 0
	v_mfma_f32_16x16x32_bf16 v[102:105], v[150:153], v[182:185], 0
	v_mfma_f32_16x16x32_bf16 v[94:97], v[142:145], v[190:193], 0
	v_mfma_f32_16x16x32_bf16 v[86:89], v[150:153], v[190:193], 0
	v_mfma_f32_16x16x32_bf16 v[78:81], v[142:145], v[198:201], 0
	v_mfma_f32_16x16x32_bf16 v[70:73], v[150:153], v[198:201], 0
	v_mfma_f32_16x16x32_bf16 v[126:129], v[146:149], v[178:181], v[126:129]
	v_mfma_f32_16x16x32_bf16 v[118:121], v[154:157], v[178:181], v[118:121]
	v_mfma_f32_16x16x32_bf16 v[110:113], v[146:149], v[186:189], v[110:113]
	v_mfma_f32_16x16x32_bf16 v[102:105], v[154:157], v[186:189], v[102:105]
	v_mfma_f32_16x16x32_bf16 v[94:97], v[146:149], v[194:197], v[94:97]
	v_mfma_f32_16x16x32_bf16 v[86:89], v[154:157], v[194:197], v[86:89]
	v_mfma_f32_16x16x32_bf16 v[78:81], v[146:149], v[202:205], v[78:81]
	v_mfma_f32_16x16x32_bf16 v[70:73], v[154:157], v[202:205], v[70:73]
	s_setprio 0
	s_setprio 1
	v_mfma_f32_16x16x32_bf16 v[122:125], v[158:161], v[174:177], 0
	v_mfma_f32_16x16x32_bf16 v[114:117], v[166:169], v[174:177], 0
	v_mfma_f32_16x16x32_bf16 v[106:109], v[158:161], v[182:185], 0
	v_mfma_f32_16x16x32_bf16 v[98:101], v[166:169], v[182:185], 0
	v_mfma_f32_16x16x32_bf16 v[90:93], v[158:161], v[190:193], 0
	v_mfma_f32_16x16x32_bf16 v[82:85], v[166:169], v[190:193], 0
	v_mfma_f32_16x16x32_bf16 v[74:77], v[158:161], v[198:201], 0
	v_mfma_f32_16x16x32_bf16 v[66:69], v[166:169], v[198:201], 0
	v_mfma_f32_16x16x32_bf16 v[122:125], v[162:165], v[178:181], v[122:125]
	v_mfma_f32_16x16x32_bf16 v[114:117], v[170:173], v[178:181], v[114:117]
	v_mfma_f32_16x16x32_bf16 v[106:109], v[162:165], v[186:189], v[106:109]
	v_mfma_f32_16x16x32_bf16 v[98:101], v[170:173], v[186:189], v[98:101]
	v_mfma_f32_16x16x32_bf16 v[90:93], v[162:165], v[194:197], v[90:93]
	v_mfma_f32_16x16x32_bf16 v[82:85], v[170:173], v[194:197], v[82:85]
	v_mfma_f32_16x16x32_bf16 v[74:77], v[162:165], v[202:205], v[74:77]
	v_mfma_f32_16x16x32_bf16 v[66:69], v[170:173], v[202:205], v[66:69]
	s_setprio 0
	s_barrier
	s_add_i32 s61, s61, s81
	v_lshl_add_u64 v[206:207], s[28:29], 0, v[0:1]
	s_mov_b32 m0, s61
	ds_read_b128 v[174:177], v140 offset:16384
	ds_read_b128 v[178:181], v140 offset:17408
	ds_read_b128 v[182:185], v140 offset:18432
	ds_read_b128 v[186:189], v140 offset:19456
	ds_read_b128 v[190:193], v140 offset:20480
	ds_read_b128 v[194:197], v140 offset:21504
	ds_read_b128 v[198:201], v140 offset:22528
	ds_read_b128 v[202:205], v140 offset:23552
	global_load_lds_dwordx4 v[206:207], off
	s_add_i32 m0, s61, 0x2000
	s_add_u32 s84, s28, 0x80000
	v_lshl_add_u64 v[208:209], s[28:29], 0, v[130:131]
	s_addc_u32 s85, s29, 0
	s_add_i32 s61, s73, s81
	global_load_lds_dwordx4 v[208:209], off
	v_lshl_add_u64 v[210:211], s[84:85], 0, v[0:1]
	s_mov_b32 m0, s61
	v_lshl_add_u64 v[212:213], s[30:31], 0, v[130:131]
	global_load_lds_dwordx4 v[210:211], off
	v_lshl_add_u64 v[210:211], s[84:85], 0, v[130:131]
	s_add_i32 m0, s61, 0x2000
	s_nop 0
	global_load_lds_dwordx4 v[210:211], off
	v_lshl_add_u64 v[210:211], s[30:31], 0, v[0:1]
	s_mov_b32 m0, s82
	s_nop 0
	global_load_lds_dwordx4 v[210:211], off
	s_mov_b32 m0, s68
	s_nop 0
	global_load_lds_dwordx4 v[212:213], off
	s_waitcnt vmcnt(8)
	s_waitcnt lgkmcnt(0)
	s_barrier
	s_setprio 1
	s_waitcnt lgkmcnt(0)
	v_mfma_f32_16x16x32_bf16 v[62:65], v[142:145], v[174:177], 0
	v_mfma_f32_16x16x32_bf16 v[54:57], v[150:153], v[174:177], 0
	v_mfma_f32_16x16x32_bf16 v[46:49], v[142:145], v[182:185], 0
	v_mfma_f32_16x16x32_bf16 v[38:41], v[150:153], v[182:185], 0
	v_mfma_f32_16x16x32_bf16 v[30:33], v[142:145], v[190:193], 0
	v_mfma_f32_16x16x32_bf16 v[22:25], v[150:153], v[190:193], 0
	v_mfma_f32_16x16x32_bf16 v[14:17], v[142:145], v[198:201], 0
	v_mfma_f32_16x16x32_bf16 v[6:9], v[150:153], v[198:201], 0
	v_mfma_f32_16x16x32_bf16 v[62:65], v[146:149], v[178:181], v[62:65]
	v_mfma_f32_16x16x32_bf16 v[54:57], v[154:157], v[178:181], v[54:57]
	v_mfma_f32_16x16x32_bf16 v[46:49], v[146:149], v[186:189], v[46:49]
	v_mfma_f32_16x16x32_bf16 v[38:41], v[154:157], v[186:189], v[38:41]
	v_mfma_f32_16x16x32_bf16 v[30:33], v[146:149], v[194:197], v[30:33]
	v_mfma_f32_16x16x32_bf16 v[22:25], v[154:157], v[194:197], v[22:25]
	v_mfma_f32_16x16x32_bf16 v[14:17], v[146:149], v[202:205], v[14:17]
	v_mfma_f32_16x16x32_bf16 v[6:9], v[154:157], v[202:205], v[6:9]
	s_setprio 0
	s_setprio 1
	v_mfma_f32_16x16x32_bf16 v[58:61], v[158:161], v[174:177], 0
	v_mfma_f32_16x16x32_bf16 v[50:53], v[166:169], v[174:177], 0
	v_mfma_f32_16x16x32_bf16 v[42:45], v[158:161], v[182:185], 0
	v_mfma_f32_16x16x32_bf16 v[34:37], v[166:169], v[182:185], 0
	v_mfma_f32_16x16x32_bf16 v[26:29], v[158:161], v[190:193], 0
	v_mfma_f32_16x16x32_bf16 v[18:21], v[166:169], v[190:193], 0
	v_mfma_f32_16x16x32_bf16 v[10:13], v[158:161], v[198:201], 0
	v_mfma_f32_16x16x32_bf16 v[2:5], v[166:169], v[198:201], 0
	v_mfma_f32_16x16x32_bf16 v[58:61], v[162:165], v[178:181], v[58:61]
	v_mfma_f32_16x16x32_bf16 v[50:53], v[170:173], v[178:181], v[50:53]
	v_mfma_f32_16x16x32_bf16 v[42:45], v[162:165], v[186:189], v[42:45]
	v_mfma_f32_16x16x32_bf16 v[34:37], v[170:173], v[186:189], v[34:37]
	v_mfma_f32_16x16x32_bf16 v[26:29], v[162:165], v[194:197], v[26:29]
	v_mfma_f32_16x16x32_bf16 v[18:21], v[170:173], v[194:197], v[18:21]
	v_mfma_f32_16x16x32_bf16 v[10:13], v[162:165], v[202:205], v[10:13]
	v_mfma_f32_16x16x32_bf16 v[2:5], v[170:173], v[202:205], v[2:5]
	s_setprio 0
	s_barrier
	s_add_i32 s61, 0, 0x18000
	v_add_u32_e32 v141, s61, v138
	s_add_i32 s73, 0, 0x1c000
	ds_read_b128 v[142:145], v141
	ds_read_b128 v[146:149], v141 offset:1024
	ds_read_b128 v[150:153], v141 offset:2048
	ds_read_b128 v[154:157], v141 offset:3072
	v_add_u32_e32 v141, s73, v138
	ds_read_b128 v[158:161], v141
	ds_read_b128 v[162:165], v141 offset:1024
	ds_read_b128 v[166:169], v141 offset:2048
	ds_read_b128 v[170:173], v141 offset:3072
	s_add_u32 s30, s30, 0x80000
	s_addc_u32 s31, s31, 0
	s_mov_b32 m0, s69
	v_lshl_add_u64 v[214:215], s[30:31], 0, v[0:1]
	ds_read_b128 v[174:177], v140 offset:32768
	ds_read_b128 v[178:181], v140 offset:33792
	ds_read_b128 v[182:185], v140 offset:34816
	ds_read_b128 v[186:189], v140 offset:35840
	ds_read_b128 v[190:193], v140 offset:36864
	ds_read_b128 v[194:197], v140 offset:37888
	ds_read_b128 v[198:201], v140 offset:38912
	ds_read_b128 v[202:205], v140 offset:39936
	global_load_lds_dwordx4 v[214:215], off
	v_lshl_add_u64 v[214:215], s[30:31], 0, v[130:131]
	s_mov_b32 m0, s70
	s_nop 0
	global_load_lds_dwordx4 v[214:215], off
	s_waitcnt vmcnt(8)
	s_waitcnt lgkmcnt(0)
	s_barrier
	s_setprio 1
	s_waitcnt lgkmcnt(0)
	v_mfma_f32_16x16x32_bf16 v[126:129], v[142:145], v[174:177], v[126:129]
	v_mfma_f32_16x16x32_bf16 v[118:121], v[150:153], v[174:177], v[118:121]
	v_mfma_f32_16x16x32_bf16 v[110:113], v[142:145], v[182:185], v[110:113]
	v_mfma_f32_16x16x32_bf16 v[102:105], v[150:153], v[182:185], v[102:105]
	v_mfma_f32_16x16x32_bf16 v[94:97], v[142:145], v[190:193], v[94:97]
	v_mfma_f32_16x16x32_bf16 v[86:89], v[150:153], v[190:193], v[86:89]
	v_mfma_f32_16x16x32_bf16 v[78:81], v[142:145], v[198:201], v[78:81]
	v_mfma_f32_16x16x32_bf16 v[70:73], v[150:153], v[198:201], v[70:73]
	v_mfma_f32_16x16x32_bf16 v[126:129], v[146:149], v[178:181], v[126:129]
	v_mfma_f32_16x16x32_bf16 v[118:121], v[154:157], v[178:181], v[118:121]
	v_mfma_f32_16x16x32_bf16 v[110:113], v[146:149], v[186:189], v[110:113]
	v_mfma_f32_16x16x32_bf16 v[102:105], v[154:157], v[186:189], v[102:105]
	v_mfma_f32_16x16x32_bf16 v[94:97], v[146:149], v[194:197], v[94:97]
	v_mfma_f32_16x16x32_bf16 v[86:89], v[154:157], v[194:197], v[86:89]
	v_mfma_f32_16x16x32_bf16 v[78:81], v[146:149], v[202:205], v[78:81]
	v_mfma_f32_16x16x32_bf16 v[70:73], v[154:157], v[202:205], v[70:73]
	s_setprio 0
	s_setprio 1
	v_mfma_f32_16x16x32_bf16 v[122:125], v[158:161], v[174:177], v[122:125]
	v_mfma_f32_16x16x32_bf16 v[114:117], v[166:169], v[174:177], v[114:117]
	v_mfma_f32_16x16x32_bf16 v[106:109], v[158:161], v[182:185], v[106:109]
	v_mfma_f32_16x16x32_bf16 v[98:101], v[166:169], v[182:185], v[98:101]
	v_mfma_f32_16x16x32_bf16 v[90:93], v[158:161], v[190:193], v[90:93]
	v_mfma_f32_16x16x32_bf16 v[82:85], v[166:169], v[190:193], v[82:85]
	v_mfma_f32_16x16x32_bf16 v[74:77], v[158:161], v[198:201], v[74:77]
	v_mfma_f32_16x16x32_bf16 v[66:69], v[166:169], v[198:201], v[66:69]
	v_mfma_f32_16x16x32_bf16 v[122:125], v[162:165], v[178:181], v[122:125]
	v_mfma_f32_16x16x32_bf16 v[114:117], v[170:173], v[178:181], v[114:117]
	v_mfma_f32_16x16x32_bf16 v[106:109], v[162:165], v[186:189], v[106:109]
	v_mfma_f32_16x16x32_bf16 v[98:101], v[170:173], v[186:189], v[98:101]
	v_mfma_f32_16x16x32_bf16 v[90:93], v[162:165], v[194:197], v[90:93]
	v_mfma_f32_16x16x32_bf16 v[82:85], v[170:173], v[194:197], v[82:85]
	v_mfma_f32_16x16x32_bf16 v[74:77], v[162:165], v[202:205], v[74:77]
	v_mfma_f32_16x16x32_bf16 v[66:69], v[170:173], v[202:205], v[66:69]
	s_setprio 0
	s_barrier
	s_add_i32 s30, s61, s81
	v_lshl_add_u64 v[206:207], v[206:207], 0, s[54:55]
	s_mov_b32 m0, s30
	ds_read_b128 v[174:177], v140 offset:49152
	ds_read_b128 v[178:181], v140 offset:50176
	ds_read_b128 v[182:185], v140 offset:51200
	ds_read_b128 v[186:189], v140 offset:52224
	ds_read_b128 v[190:193], v140 offset:53248
	ds_read_b128 v[194:197], v140 offset:54272
	ds_read_b128 v[198:201], v140 offset:55296
	ds_read_b128 v[202:205], v140 offset:56320
	global_load_lds_dwordx4 v[206:207], off
	s_add_i32 m0, s30, 0x2000
	s_add_u32 s28, s28, 0x80080
	v_lshl_add_u64 v[206:207], v[208:209], 0, s[54:55]
	s_addc_u32 s29, s29, 0
	s_add_i32 s30, s73, s81
	global_load_lds_dwordx4 v[206:207], off
	v_lshl_add_u64 v[206:207], s[28:29], 0, v[0:1]
	s_mov_b32 m0, s30
	s_nop 0
	global_load_lds_dwordx4 v[206:207], off
	v_lshl_add_u64 v[206:207], s[28:29], 0, v[130:131]
	s_add_i32 m0, s30, 0x2000
	s_nop 0
	global_load_lds_dwordx4 v[206:207], off
	v_lshl_add_u64 v[206:207], v[210:211], 0, s[54:55]
	s_mov_b32 m0, s71
	s_nop 0
	global_load_lds_dwordx4 v[206:207], off
	v_lshl_add_u64 v[206:207], v[212:213], 0, s[54:55]
	s_mov_b32 m0, s72
	s_nop 0
	global_load_lds_dwordx4 v[206:207], off
	s_waitcnt vmcnt(8)
	s_waitcnt lgkmcnt(0)
	s_barrier
	s_setprio 1
	s_waitcnt lgkmcnt(0)
	v_mfma_f32_16x16x32_bf16 v[62:65], v[142:145], v[174:177], v[62:65]
	v_mfma_f32_16x16x32_bf16 v[54:57], v[150:153], v[174:177], v[54:57]
	v_mfma_f32_16x16x32_bf16 v[46:49], v[142:145], v[182:185], v[46:49]
	v_mfma_f32_16x16x32_bf16 v[38:41], v[150:153], v[182:185], v[38:41]
	v_mfma_f32_16x16x32_bf16 v[30:33], v[142:145], v[190:193], v[30:33]
	v_mfma_f32_16x16x32_bf16 v[22:25], v[150:153], v[190:193], v[22:25]
	v_mfma_f32_16x16x32_bf16 v[14:17], v[142:145], v[198:201], v[14:17]
	v_mfma_f32_16x16x32_bf16 v[6:9], v[150:153], v[198:201], v[6:9]
	v_mfma_f32_16x16x32_bf16 v[62:65], v[146:149], v[178:181], v[62:65]
	v_mfma_f32_16x16x32_bf16 v[54:57], v[154:157], v[178:181], v[54:57]
	v_mfma_f32_16x16x32_bf16 v[46:49], v[146:149], v[186:189], v[46:49]
	v_mfma_f32_16x16x32_bf16 v[38:41], v[154:157], v[186:189], v[38:41]
	v_mfma_f32_16x16x32_bf16 v[30:33], v[146:149], v[194:197], v[30:33]
	v_mfma_f32_16x16x32_bf16 v[22:25], v[154:157], v[194:197], v[22:25]
	v_mfma_f32_16x16x32_bf16 v[14:17], v[146:149], v[202:205], v[14:17]
	v_mfma_f32_16x16x32_bf16 v[6:9], v[154:157], v[202:205], v[6:9]
	s_setprio 0
	s_setprio 1
	v_mfma_f32_16x16x32_bf16 v[58:61], v[158:161], v[174:177], v[58:61]
	v_mfma_f32_16x16x32_bf16 v[50:53], v[166:169], v[174:177], v[50:53]
	v_mfma_f32_16x16x32_bf16 v[42:45], v[158:161], v[182:185], v[42:45]
	v_mfma_f32_16x16x32_bf16 v[34:37], v[166:169], v[182:185], v[34:37]
	v_mfma_f32_16x16x32_bf16 v[26:29], v[158:161], v[190:193], v[26:29]
	v_mfma_f32_16x16x32_bf16 v[18:21], v[166:169], v[190:193], v[18:21]
	v_mfma_f32_16x16x32_bf16 v[10:13], v[158:161], v[198:201], v[10:13]
	v_mfma_f32_16x16x32_bf16 v[2:5], v[166:169], v[198:201], v[2:5]
	v_mfma_f32_16x16x32_bf16 v[58:61], v[162:165], v[178:181], v[58:61]
	v_mfma_f32_16x16x32_bf16 v[50:53], v[170:173], v[178:181], v[50:53]
	v_mfma_f32_16x16x32_bf16 v[42:45], v[162:165], v[186:189], v[42:45]
	v_mfma_f32_16x16x32_bf16 v[34:37], v[170:173], v[186:189], v[34:37]
	v_mfma_f32_16x16x32_bf16 v[26:29], v[162:165], v[194:197], v[26:29]
	v_mfma_f32_16x16x32_bf16 v[18:21], v[170:173], v[194:197], v[18:21]
	v_mfma_f32_16x16x32_bf16 v[10:13], v[162:165], v[202:205], v[10:13]
	v_mfma_f32_16x16x32_bf16 v[2:5], v[170:173], v[202:205], v[2:5]
	s_setprio 0
	s_barrier
	s_add_i32 s49, s49, 2
	s_add_u32 s45, s45, 0x100
	s_addc_u32 s48, s48, 0
	s_add_u32 s26, s26, 0x100
	s_addc_u32 s27, s27, 0
	s_cmp_gt_u32 s49, 29
	s_cbranch_scc1 .Lpeel_exit_G3
	s_branch .LBB0_1060
